# nt (streaming) hint on the 8 SwiGLU ACT stores, to shrink the dirty-L2 writeback at the grid barrier
# baseline (speedup 1.0000x reference)
.LBB0_255:
	v_mov_b32_e32 v178, 0xbfb8aa3b
	v_mov_b32_e32 v179, 0xbfb8aa3b
	s_lshl_b32 s11, s18, 8
	s_mov_b64 s[18:19], -1
	ds_read_b32 v182, v170
	ds_read_b32 v183, v170 offset:64
	ds_read_b32 v184, v170 offset:128
	ds_read_b32 v185, v170 offset:192
	ds_read_b32 v186, v170 offset:512
	ds_read_b32 v187, v170 offset:576
	ds_read_b32 v188, v170 offset:640
	ds_read_b32 v189, v170 offset:704
	v_add_u32_e32 v203, s11, v166
	v_lshl_or_b32 v202, s60, 7, v171
	v_lshlrev_b32_e32 v202, 1, v202
	v_mad_u32_u24 v202, v203, s86, v202
	s_waitcnt lgkmcnt(0)
	v_pk_fma_f32 v[132:133], v[132:133], v[182:183], v[238:239] op_sel_hi:[1,0,1]
	v_pk_fma_f32 v[134:135], v[134:135], v[182:183], v[240:241] op_sel_hi:[1,0,1]
	v_pk_fma_f32 v[124:125], v[124:125], v[182:183], v[242:243] op_sel_hi:[1,0,1]
	v_pk_fma_f32 v[126:127], v[126:127], v[182:183], v[244:245] op_sel_hi:[1,0,1]
	v_pk_fma_f32 v[128:129], v[128:129], v[182:183], v[246:247] op_sel_hi:[1,0,1]
	v_pk_fma_f32 v[130:131], v[130:131], v[182:183], v[248:249] op_sel_hi:[1,0,1]
	v_pk_fma_f32 v[120:121], v[120:121], v[182:183], v[250:251] op_sel_hi:[1,0,1]
	v_pk_fma_f32 v[122:123], v[122:123], v[182:183], v[252:253] op_sel_hi:[1,0,1]
	v_pk_mul_f32 v[190:191], v[132:133], v[178:179]
	v_pk_mul_f32 v[192:193], v[134:135], v[178:179]
	v_pk_mul_f32 v[194:195], v[124:125], v[178:179]
	v_pk_mul_f32 v[196:197], v[126:127], v[178:179]
	v_exp_f32_e32 v190, v190
	v_exp_f32_e32 v191, v191
	v_exp_f32_e32 v192, v192
	v_exp_f32_e32 v193, v193
	v_exp_f32_e32 v194, v194
	v_exp_f32_e32 v195, v195
	v_exp_f32_e32 v196, v196
	v_exp_f32_e32 v197, v197
	v_pk_add_f32 v[190:191], v[190:191], 1.0 op_sel_hi:[1,0]
	v_pk_add_f32 v[192:193], v[192:193], 1.0 op_sel_hi:[1,0]
	v_pk_add_f32 v[194:195], v[194:195], 1.0 op_sel_hi:[1,0]
	v_pk_add_f32 v[196:197], v[196:197], 1.0 op_sel_hi:[1,0]
	v_rcp_f32_e32 v190, v190
	v_rcp_f32_e32 v191, v191
	v_rcp_f32_e32 v192, v192
	v_rcp_f32_e32 v193, v193
	v_rcp_f32_e32 v194, v194
	v_rcp_f32_e32 v195, v195
	v_rcp_f32_e32 v196, v196
	v_rcp_f32_e32 v197, v197
	v_pk_mul_f32 v[132:133], v[132:133], v[190:191]
	v_pk_mul_f32 v[134:135], v[134:135], v[192:193]
	v_pk_mul_f32 v[124:125], v[124:125], v[194:195]
	v_pk_mul_f32 v[126:127], v[126:127], v[196:197]
	v_pk_mul_f32 v[132:133], v[132:133], v[128:129]
	v_pk_mul_f32 v[134:135], v[134:135], v[130:131]
	v_pk_mul_f32 v[124:125], v[124:125], v[120:121]
	v_pk_mul_f32 v[126:127], v[126:127], v[122:123]
	v_cvt_pk_bf16_f32 v198, v132, v133
	v_cvt_pk_bf16_f32 v199, v134, v135
	v_cvt_pk_bf16_f32 v200, v124, v125
	v_cvt_pk_bf16_f32 v201, v126, v127
	global_store_dwordx4 v202, v[198:201], s[6:7] nt
	v_pk_fma_f32 v[116:117], v[116:117], v[182:183], v[238:239] op_sel:[0,1,0] op_sel_hi:[1,1,1]
	v_pk_fma_f32 v[118:119], v[118:119], v[182:183], v[240:241] op_sel:[0,1,0] op_sel_hi:[1,1,1]
	v_pk_fma_f32 v[112:113], v[112:113], v[182:183], v[242:243] op_sel:[0,1,0] op_sel_hi:[1,1,1]
	v_pk_fma_f32 v[114:115], v[114:115], v[182:183], v[244:245] op_sel:[0,1,0] op_sel_hi:[1,1,1]
	v_pk_fma_f32 v[108:109], v[108:109], v[182:183], v[246:247] op_sel:[0,1,0] op_sel_hi:[1,1,1]
	v_pk_fma_f32 v[110:111], v[110:111], v[182:183], v[248:249] op_sel:[0,1,0] op_sel_hi:[1,1,1]
	v_pk_fma_f32 v[104:105], v[104:105], v[182:183], v[250:251] op_sel:[0,1,0] op_sel_hi:[1,1,1]
	v_pk_fma_f32 v[106:107], v[106:107], v[182:183], v[252:253] op_sel:[0,1,0] op_sel_hi:[1,1,1]
	v_pk_mul_f32 v[190:191], v[116:117], v[178:179]
	v_pk_mul_f32 v[192:193], v[118:119], v[178:179]
	v_pk_mul_f32 v[194:195], v[112:113], v[178:179]
	v_pk_mul_f32 v[196:197], v[114:115], v[178:179]
	v_exp_f32_e32 v190, v190
	v_exp_f32_e32 v191, v191
	v_exp_f32_e32 v192, v192
	v_exp_f32_e32 v193, v193
	v_exp_f32_e32 v194, v194
	v_exp_f32_e32 v195, v195
	v_exp_f32_e32 v196, v196
	v_exp_f32_e32 v197, v197
	v_pk_add_f32 v[190:191], v[190:191], 1.0 op_sel_hi:[1,0]
	v_pk_add_f32 v[192:193], v[192:193], 1.0 op_sel_hi:[1,0]
	v_pk_add_f32 v[194:195], v[194:195], 1.0 op_sel_hi:[1,0]
	v_pk_add_f32 v[196:197], v[196:197], 1.0 op_sel_hi:[1,0]
	v_rcp_f32_e32 v190, v190
	v_rcp_f32_e32 v191, v191
	v_rcp_f32_e32 v192, v192
	v_rcp_f32_e32 v193, v193
	v_rcp_f32_e32 v194, v194
	v_rcp_f32_e32 v195, v195
	v_rcp_f32_e32 v196, v196
	v_rcp_f32_e32 v197, v197
	v_pk_mul_f32 v[116:117], v[116:117], v[190:191]
	v_pk_mul_f32 v[118:119], v[118:119], v[192:193]
	v_pk_mul_f32 v[112:113], v[112:113], v[194:195]
	v_pk_mul_f32 v[114:115], v[114:115], v[196:197]
	v_pk_mul_f32 v[116:117], v[116:117], v[108:109]
	v_pk_mul_f32 v[118:119], v[118:119], v[110:111]
	v_pk_mul_f32 v[112:113], v[112:113], v[104:105]
	v_pk_mul_f32 v[114:115], v[114:115], v[106:107]
	v_cvt_pk_bf16_f32 v198, v116, v117
	v_cvt_pk_bf16_f32 v199, v118, v119
	v_cvt_pk_bf16_f32 v200, v112, v113
	v_cvt_pk_bf16_f32 v201, v114, v115
	v_add_u32_e32 v203, 0x16000, v202
	s_nop 0
	global_store_dwordx4 v203, v[198:201], s[6:7] nt
	v_pk_fma_f32 v[100:101], v[100:101], v[184:185], v[238:239] op_sel_hi:[1,0,1]
	v_pk_fma_f32 v[102:103], v[102:103], v[184:185], v[240:241] op_sel_hi:[1,0,1]
	v_pk_fma_f32 v[96:97], v[96:97], v[184:185], v[242:243] op_sel_hi:[1,0,1]
	v_pk_fma_f32 v[98:99], v[98:99], v[184:185], v[244:245] op_sel_hi:[1,0,1]
	v_pk_fma_f32 v[92:93], v[92:93], v[184:185], v[246:247] op_sel_hi:[1,0,1]
	v_pk_fma_f32 v[94:95], v[94:95], v[184:185], v[248:249] op_sel_hi:[1,0,1]
	v_pk_fma_f32 v[88:89], v[88:89], v[184:185], v[250:251] op_sel_hi:[1,0,1]
	v_pk_fma_f32 v[90:91], v[90:91], v[184:185], v[252:253] op_sel_hi:[1,0,1]
	v_pk_mul_f32 v[190:191], v[100:101], v[178:179]
	v_pk_mul_f32 v[192:193], v[102:103], v[178:179]
	v_pk_mul_f32 v[194:195], v[96:97], v[178:179]
	v_pk_mul_f32 v[196:197], v[98:99], v[178:179]
	v_exp_f32_e32 v190, v190
	v_exp_f32_e32 v191, v191
	v_exp_f32_e32 v192, v192
	v_exp_f32_e32 v193, v193
	v_exp_f32_e32 v194, v194
	v_exp_f32_e32 v195, v195
	v_exp_f32_e32 v196, v196
	v_exp_f32_e32 v197, v197
	v_pk_add_f32 v[190:191], v[190:191], 1.0 op_sel_hi:[1,0]
	v_pk_add_f32 v[192:193], v[192:193], 1.0 op_sel_hi:[1,0]
	v_pk_add_f32 v[194:195], v[194:195], 1.0 op_sel_hi:[1,0]
	v_pk_add_f32 v[196:197], v[196:197], 1.0 op_sel_hi:[1,0]
	v_rcp_f32_e32 v190, v190
	v_rcp_f32_e32 v191, v191
	v_rcp_f32_e32 v192, v192
	v_rcp_f32_e32 v193, v193
	v_rcp_f32_e32 v194, v194
	v_rcp_f32_e32 v195, v195
	v_rcp_f32_e32 v196, v196
	v_rcp_f32_e32 v197, v197
	v_pk_mul_f32 v[100:101], v[100:101], v[190:191]
	v_pk_mul_f32 v[102:103], v[102:103], v[192:193]
	v_pk_mul_f32 v[96:97], v[96:97], v[194:195]
	v_pk_mul_f32 v[98:99], v[98:99], v[196:197]
	v_pk_mul_f32 v[100:101], v[100:101], v[92:93]
	v_pk_mul_f32 v[102:103], v[102:103], v[94:95]
	v_pk_mul_f32 v[96:97], v[96:97], v[88:89]
	v_pk_mul_f32 v[98:99], v[98:99], v[90:91]
	v_cvt_pk_bf16_f32 v198, v100, v101
	v_cvt_pk_bf16_f32 v199, v102, v103
	v_cvt_pk_bf16_f32 v200, v96, v97
	v_cvt_pk_bf16_f32 v201, v98, v99
	v_add_u32_e32 v203, 0x2c000, v202
	s_nop 0
	global_store_dwordx4 v203, v[198:201], s[6:7] nt
	v_pk_fma_f32 v[84:85], v[84:85], v[184:185], v[238:239] op_sel:[0,1,0] op_sel_hi:[1,1,1]
	v_pk_fma_f32 v[86:87], v[86:87], v[184:185], v[240:241] op_sel:[0,1,0] op_sel_hi:[1,1,1]
	v_pk_fma_f32 v[80:81], v[80:81], v[184:185], v[242:243] op_sel:[0,1,0] op_sel_hi:[1,1,1]
	v_pk_fma_f32 v[82:83], v[82:83], v[184:185], v[244:245] op_sel:[0,1,0] op_sel_hi:[1,1,1]
	v_pk_fma_f32 v[76:77], v[76:77], v[184:185], v[246:247] op_sel:[0,1,0] op_sel_hi:[1,1,1]
	v_pk_fma_f32 v[78:79], v[78:79], v[184:185], v[248:249] op_sel:[0,1,0] op_sel_hi:[1,1,1]
	v_pk_fma_f32 v[72:73], v[72:73], v[184:185], v[250:251] op_sel:[0,1,0] op_sel_hi:[1,1,1]
	v_pk_fma_f32 v[74:75], v[74:75], v[184:185], v[252:253] op_sel:[0,1,0] op_sel_hi:[1,1,1]
	v_pk_mul_f32 v[190:191], v[84:85], v[178:179]
	v_pk_mul_f32 v[192:193], v[86:87], v[178:179]
	v_pk_mul_f32 v[194:195], v[80:81], v[178:179]
	v_pk_mul_f32 v[196:197], v[82:83], v[178:179]
	v_exp_f32_e32 v190, v190
	v_exp_f32_e32 v191, v191
	v_exp_f32_e32 v192, v192
	v_exp_f32_e32 v193, v193
	v_exp_f32_e32 v194, v194
	v_exp_f32_e32 v195, v195
	v_exp_f32_e32 v196, v196
	v_exp_f32_e32 v197, v197
	v_pk_add_f32 v[190:191], v[190:191], 1.0 op_sel_hi:[1,0]
	v_pk_add_f32 v[192:193], v[192:193], 1.0 op_sel_hi:[1,0]
	v_pk_add_f32 v[194:195], v[194:195], 1.0 op_sel_hi:[1,0]
	v_pk_add_f32 v[196:197], v[196:197], 1.0 op_sel_hi:[1,0]
	v_rcp_f32_e32 v190, v190
	v_rcp_f32_e32 v191, v191
	v_rcp_f32_e32 v192, v192
	v_rcp_f32_e32 v193, v193
	v_rcp_f32_e32 v194, v194
	v_rcp_f32_e32 v195, v195
	v_rcp_f32_e32 v196, v196
	v_rcp_f32_e32 v197, v197
	v_pk_mul_f32 v[84:85], v[84:85], v[190:191]
	v_pk_mul_f32 v[86:87], v[86:87], v[192:193]
	v_pk_mul_f32 v[80:81], v[80:81], v[194:195]
	v_pk_mul_f32 v[82:83], v[82:83], v[196:197]
	v_pk_mul_f32 v[84:85], v[84:85], v[76:77]
	v_pk_mul_f32 v[86:87], v[86:87], v[78:79]
	v_pk_mul_f32 v[80:81], v[80:81], v[72:73]
	v_pk_mul_f32 v[82:83], v[82:83], v[74:75]
	v_cvt_pk_bf16_f32 v198, v84, v85
	v_cvt_pk_bf16_f32 v199, v86, v87
	v_cvt_pk_bf16_f32 v200, v80, v81
	v_cvt_pk_bf16_f32 v201, v82, v83
	v_add_u32_e32 v203, 0x42000, v202
	s_nop 0
	global_store_dwordx4 v203, v[198:201], s[6:7] nt
	v_pk_fma_f32 v[68:69], v[68:69], v[186:187], v[238:239] op_sel_hi:[1,0,1]
	v_pk_fma_f32 v[70:71], v[70:71], v[186:187], v[240:241] op_sel_hi:[1,0,1]
	v_pk_fma_f32 v[64:65], v[64:65], v[186:187], v[242:243] op_sel_hi:[1,0,1]
	v_pk_fma_f32 v[66:67], v[66:67], v[186:187], v[244:245] op_sel_hi:[1,0,1]
	v_pk_fma_f32 v[60:61], v[60:61], v[186:187], v[246:247] op_sel_hi:[1,0,1]
	v_pk_fma_f32 v[62:63], v[62:63], v[186:187], v[248:249] op_sel_hi:[1,0,1]
	v_pk_fma_f32 v[52:53], v[52:53], v[186:187], v[250:251] op_sel_hi:[1,0,1]
	v_pk_fma_f32 v[54:55], v[54:55], v[186:187], v[252:253] op_sel_hi:[1,0,1]
	v_pk_mul_f32 v[190:191], v[68:69], v[178:179]
	v_pk_mul_f32 v[192:193], v[70:71], v[178:179]
	v_pk_mul_f32 v[194:195], v[64:65], v[178:179]
	v_pk_mul_f32 v[196:197], v[66:67], v[178:179]
	v_exp_f32_e32 v190, v190
	v_exp_f32_e32 v191, v191
	v_exp_f32_e32 v192, v192
	v_exp_f32_e32 v193, v193
	v_exp_f32_e32 v194, v194
	v_exp_f32_e32 v195, v195
	v_exp_f32_e32 v196, v196
	v_exp_f32_e32 v197, v197
	v_pk_add_f32 v[190:191], v[190:191], 1.0 op_sel_hi:[1,0]
	v_pk_add_f32 v[192:193], v[192:193], 1.0 op_sel_hi:[1,0]
	v_pk_add_f32 v[194:195], v[194:195], 1.0 op_sel_hi:[1,0]
	v_pk_add_f32 v[196:197], v[196:197], 1.0 op_sel_hi:[1,0]
	v_rcp_f32_e32 v190, v190
	v_rcp_f32_e32 v191, v191
	v_rcp_f32_e32 v192, v192
	v_rcp_f32_e32 v193, v193
	v_rcp_f32_e32 v194, v194
	v_rcp_f32_e32 v195, v195
	v_rcp_f32_e32 v196, v196
	v_rcp_f32_e32 v197, v197
	v_pk_mul_f32 v[68:69], v[68:69], v[190:191]
	v_pk_mul_f32 v[70:71], v[70:71], v[192:193]
	v_pk_mul_f32 v[64:65], v[64:65], v[194:195]
	v_pk_mul_f32 v[66:67], v[66:67], v[196:197]
	v_pk_mul_f32 v[68:69], v[68:69], v[60:61]
	v_pk_mul_f32 v[70:71], v[70:71], v[62:63]
	v_pk_mul_f32 v[64:65], v[64:65], v[52:53]
	v_pk_mul_f32 v[66:67], v[66:67], v[54:55]
	v_cvt_pk_bf16_f32 v198, v68, v69
	v_cvt_pk_bf16_f32 v199, v70, v71
	v_cvt_pk_bf16_f32 v200, v64, v65
	v_cvt_pk_bf16_f32 v201, v66, v67
	v_add_u32_e32 v203, 0xb0000, v202
	s_nop 0
	global_store_dwordx4 v203, v[198:201], s[6:7] nt
	v_pk_fma_f32 v[44:45], v[44:45], v[186:187], v[238:239] op_sel:[0,1,0] op_sel_hi:[1,1,1]
	v_pk_fma_f32 v[46:47], v[46:47], v[186:187], v[240:241] op_sel:[0,1,0] op_sel_hi:[1,1,1]
	v_pk_fma_f32 v[40:41], v[40:41], v[186:187], v[242:243] op_sel:[0,1,0] op_sel_hi:[1,1,1]
	v_pk_fma_f32 v[42:43], v[42:43], v[186:187], v[244:245] op_sel:[0,1,0] op_sel_hi:[1,1,1]
	v_pk_fma_f32 v[36:37], v[36:37], v[186:187], v[246:247] op_sel:[0,1,0] op_sel_hi:[1,1,1]
	v_pk_fma_f32 v[38:39], v[38:39], v[186:187], v[248:249] op_sel:[0,1,0] op_sel_hi:[1,1,1]
	v_pk_fma_f32 v[32:33], v[32:33], v[186:187], v[250:251] op_sel:[0,1,0] op_sel_hi:[1,1,1]
	v_pk_fma_f32 v[34:35], v[34:35], v[186:187], v[252:253] op_sel:[0,1,0] op_sel_hi:[1,1,1]
	v_pk_mul_f32 v[190:191], v[44:45], v[178:179]
	v_pk_mul_f32 v[192:193], v[46:47], v[178:179]
	v_pk_mul_f32 v[194:195], v[40:41], v[178:179]
	v_pk_mul_f32 v[196:197], v[42:43], v[178:179]
	v_exp_f32_e32 v190, v190
	v_exp_f32_e32 v191, v191
	v_exp_f32_e32 v192, v192
	v_exp_f32_e32 v193, v193
	v_exp_f32_e32 v194, v194
	v_exp_f32_e32 v195, v195
	v_exp_f32_e32 v196, v196
	v_exp_f32_e32 v197, v197
	v_pk_add_f32 v[190:191], v[190:191], 1.0 op_sel_hi:[1,0]
	v_pk_add_f32 v[192:193], v[192:193], 1.0 op_sel_hi:[1,0]
	v_pk_add_f32 v[194:195], v[194:195], 1.0 op_sel_hi:[1,0]
	v_pk_add_f32 v[196:197], v[196:197], 1.0 op_sel_hi:[1,0]
	v_rcp_f32_e32 v190, v190
	v_rcp_f32_e32 v191, v191
	v_rcp_f32_e32 v192, v192
	v_rcp_f32_e32 v193, v193
	v_rcp_f32_e32 v194, v194
	v_rcp_f32_e32 v195, v195
	v_rcp_f32_e32 v196, v196
	v_rcp_f32_e32 v197, v197
	v_pk_mul_f32 v[44:45], v[44:45], v[190:191]
	v_pk_mul_f32 v[46:47], v[46:47], v[192:193]
	v_pk_mul_f32 v[40:41], v[40:41], v[194:195]
	v_pk_mul_f32 v[42:43], v[42:43], v[196:197]
	v_pk_mul_f32 v[44:45], v[44:45], v[36:37]
	v_pk_mul_f32 v[46:47], v[46:47], v[38:39]
	v_pk_mul_f32 v[40:41], v[40:41], v[32:33]
	v_pk_mul_f32 v[42:43], v[42:43], v[34:35]
	v_cvt_pk_bf16_f32 v198, v44, v45
	v_cvt_pk_bf16_f32 v199, v46, v47
	v_cvt_pk_bf16_f32 v200, v40, v41
	v_cvt_pk_bf16_f32 v201, v42, v43
	v_add_u32_e32 v203, 0xc6000, v202
	s_nop 0
	global_store_dwordx4 v203, v[198:201], s[6:7] nt
	v_pk_fma_f32 v[28:29], v[28:29], v[188:189], v[238:239] op_sel_hi:[1,0,1]
	v_pk_fma_f32 v[30:31], v[30:31], v[188:189], v[240:241] op_sel_hi:[1,0,1]
	v_pk_fma_f32 v[24:25], v[24:25], v[188:189], v[242:243] op_sel_hi:[1,0,1]
	v_pk_fma_f32 v[26:27], v[26:27], v[188:189], v[244:245] op_sel_hi:[1,0,1]
	v_pk_fma_f32 v[20:21], v[20:21], v[188:189], v[246:247] op_sel_hi:[1,0,1]
	v_pk_fma_f32 v[22:23], v[22:23], v[188:189], v[248:249] op_sel_hi:[1,0,1]
	v_pk_fma_f32 v[16:17], v[16:17], v[188:189], v[250:251] op_sel_hi:[1,0,1]
	v_pk_fma_f32 v[18:19], v[18:19], v[188:189], v[252:253] op_sel_hi:[1,0,1]
	v_pk_mul_f32 v[190:191], v[28:29], v[178:179]
	v_pk_mul_f32 v[192:193], v[30:31], v[178:179]
	v_pk_mul_f32 v[194:195], v[24:25], v[178:179]
	v_pk_mul_f32 v[196:197], v[26:27], v[178:179]
	v_exp_f32_e32 v190, v190
	v_exp_f32_e32 v191, v191
	v_exp_f32_e32 v192, v192
	v_exp_f32_e32 v193, v193
	v_exp_f32_e32 v194, v194
	v_exp_f32_e32 v195, v195
	v_exp_f32_e32 v196, v196
	v_exp_f32_e32 v197, v197
	v_pk_add_f32 v[190:191], v[190:191], 1.0 op_sel_hi:[1,0]
	v_pk_add_f32 v[192:193], v[192:193], 1.0 op_sel_hi:[1,0]
	v_pk_add_f32 v[194:195], v[194:195], 1.0 op_sel_hi:[1,0]
	v_pk_add_f32 v[196:197], v[196:197], 1.0 op_sel_hi:[1,0]
	v_rcp_f32_e32 v190, v190
	v_rcp_f32_e32 v191, v191
	v_rcp_f32_e32 v192, v192
	v_rcp_f32_e32 v193, v193
	v_rcp_f32_e32 v194, v194
	v_rcp_f32_e32 v195, v195
	v_rcp_f32_e32 v196, v196
	v_rcp_f32_e32 v197, v197
	v_pk_mul_f32 v[28:29], v[28:29], v[190:191]
	v_pk_mul_f32 v[30:31], v[30:31], v[192:193]
	v_pk_mul_f32 v[24:25], v[24:25], v[194:195]
	v_pk_mul_f32 v[26:27], v[26:27], v[196:197]
	v_pk_mul_f32 v[28:29], v[28:29], v[20:21]
	v_pk_mul_f32 v[30:31], v[30:31], v[22:23]
	v_pk_mul_f32 v[24:25], v[24:25], v[16:17]
	v_pk_mul_f32 v[26:27], v[26:27], v[18:19]
	v_cvt_pk_bf16_f32 v198, v28, v29
	v_cvt_pk_bf16_f32 v199, v30, v31
	v_cvt_pk_bf16_f32 v200, v24, v25
	v_cvt_pk_bf16_f32 v201, v26, v27
	v_add_u32_e32 v203, 0xdc000, v202
	s_nop 0
	global_store_dwordx4 v203, v[198:201], s[6:7] nt
	v_pk_fma_f32 v[12:13], v[12:13], v[188:189], v[238:239] op_sel:[0,1,0] op_sel_hi:[1,1,1]
	v_pk_fma_f32 v[14:15], v[14:15], v[188:189], v[240:241] op_sel:[0,1,0] op_sel_hi:[1,1,1]
	v_pk_fma_f32 v[8:9], v[8:9], v[188:189], v[242:243] op_sel:[0,1,0] op_sel_hi:[1,1,1]
	v_pk_fma_f32 v[10:11], v[10:11], v[188:189], v[244:245] op_sel:[0,1,0] op_sel_hi:[1,1,1]
	v_pk_fma_f32 v[4:5], v[4:5], v[188:189], v[246:247] op_sel:[0,1,0] op_sel_hi:[1,1,1]
	v_pk_fma_f32 v[6:7], v[6:7], v[188:189], v[248:249] op_sel:[0,1,0] op_sel_hi:[1,1,1]
	v_pk_fma_f32 v[0:1], v[0:1], v[188:189], v[250:251] op_sel:[0,1,0] op_sel_hi:[1,1,1]
	v_pk_fma_f32 v[2:3], v[2:3], v[188:189], v[252:253] op_sel:[0,1,0] op_sel_hi:[1,1,1]
	v_pk_mul_f32 v[190:191], v[12:13], v[178:179]
	v_pk_mul_f32 v[192:193], v[14:15], v[178:179]
	v_pk_mul_f32 v[194:195], v[8:9], v[178:179]
	v_pk_mul_f32 v[196:197], v[10:11], v[178:179]
	v_exp_f32_e32 v190, v190
	v_exp_f32_e32 v191, v191
	v_exp_f32_e32 v192, v192
	v_exp_f32_e32 v193, v193
	v_exp_f32_e32 v194, v194
	v_exp_f32_e32 v195, v195
	v_exp_f32_e32 v196, v196
	v_exp_f32_e32 v197, v197
	v_pk_add_f32 v[190:191], v[190:191], 1.0 op_sel_hi:[1,0]
	v_pk_add_f32 v[192:193], v[192:193], 1.0 op_sel_hi:[1,0]
	v_pk_add_f32 v[194:195], v[194:195], 1.0 op_sel_hi:[1,0]
	v_pk_add_f32 v[196:197], v[196:197], 1.0 op_sel_hi:[1,0]
	v_rcp_f32_e32 v190, v190
	v_rcp_f32_e32 v191, v191
	v_rcp_f32_e32 v192, v192
	v_rcp_f32_e32 v193, v193
	v_rcp_f32_e32 v194, v194
	v_rcp_f32_e32 v195, v195
	v_rcp_f32_e32 v196, v196
	v_rcp_f32_e32 v197, v197
	v_pk_mul_f32 v[12:13], v[12:13], v[190:191]
	v_pk_mul_f32 v[14:15], v[14:15], v[192:193]
	v_pk_mul_f32 v[8:9], v[8:9], v[194:195]
	v_pk_mul_f32 v[10:11], v[10:11], v[196:197]
	v_pk_mul_f32 v[12:13], v[12:13], v[4:5]
	v_pk_mul_f32 v[14:15], v[14:15], v[6:7]
	v_pk_mul_f32 v[8:9], v[8:9], v[0:1]
	v_pk_mul_f32 v[10:11], v[10:11], v[2:3]
	v_cvt_pk_bf16_f32 v198, v12, v13
	v_cvt_pk_bf16_f32 v199, v14, v15
	v_cvt_pk_bf16_f32 v200, v8, v9
	v_cvt_pk_bf16_f32 v201, v10, v11
	v_add_u32_e32 v203, 0xf2000, v202
	s_nop 0
	global_store_dwordx4 v203, v[198:201], s[6:7] nt
	s_andn2_b64 vcc, exec, s[4:5]
	s_cbranch_vccnz .LBB0_248
	s_andn2_b64 vcc, exec, s[0:1]
	s_cbranch_vccnz .LBB0_247
	s_barrier
	s_branch .LBB0_247
